# residual GEMM epilogues (w_o, down) rewritten straight-line: gate vectors once per tile, residual loads 8 x dwordx4 ahead of the fma+store stream with counted vmcnt waits, no per-row-group exec-masked
# speedup vs baseline: 1.0383x; 1.0114x over previous
.LBB0_984:
	s_add_i32 s52, s52, 2
	s_cmp_lg_u32 s52, 16
	s_waitcnt lgkmcnt(0)
	s_mov_b32 s98, 1
	s_cbranch_scc1 .LBB0_959
	s_mov_b32 s98, 0
	v_mfma_f32_16x16x32_bf16 v[98:101], v[210:213], v[178:181], v[98:101]
	v_mfma_f32_16x16x32_bf16 v[94:97], v[214:217], v[178:181], v[94:97]
	v_mfma_f32_16x16x32_bf16 v[90:93], v[218:221], v[178:181], v[90:93]
	v_mfma_f32_16x16x32_bf16 v[86:89], v[222:225], v[178:181], v[86:89]
	v_mfma_f32_16x16x32_bf16 v[78:81], v[210:213], v[182:185], v[78:81]
	v_mfma_f32_16x16x32_bf16 v[74:77], v[214:217], v[182:185], v[74:77]
	v_mfma_f32_16x16x32_bf16 v[70:73], v[218:221], v[182:185], v[70:73]
	v_mfma_f32_16x16x32_bf16 v[66:69], v[222:225], v[182:185], v[66:69]
	v_mfma_f32_16x16x32_bf16 v[62:65], v[210:213], v[186:189], v[62:65]
	v_mfma_f32_16x16x32_bf16 v[58:61], v[214:217], v[186:189], v[58:61]
	v_mfma_f32_16x16x32_bf16 v[54:57], v[218:221], v[186:189], v[54:57]
	v_mfma_f32_16x16x32_bf16 v[50:53], v[222:225], v[186:189], v[50:53]
	v_mfma_f32_16x16x32_bf16 v[46:49], v[210:213], v[190:193], v[46:49]
	v_mfma_f32_16x16x32_bf16 v[42:45], v[214:217], v[190:193], v[42:45]
	v_mfma_f32_16x16x32_bf16 v[38:41], v[218:221], v[190:193], v[38:41]
	v_mfma_f32_16x16x32_bf16 v[34:37], v[222:225], v[190:193], v[34:37]
	s_nop 7
	s_nop 7
	v_mov_b32_e32 v172, v0
	s_nop 0
	v_ashrrev_i32_e32 v162, 1, v172
	v_and_b32_e32 v162, 0xffffff80, v162
	v_lshl_add_u32 v162, s38, 8, v162
	v_and_or_b32 v164, v172, 15, v162
	v_add_u32_e32 v162, 0xffffe000, v162
	v_ashrrev_i32_e32 v162, 11, v162
	v_mad_i32_i24 v162, v162, s47, s47
	v_cmp_lt_i32_e32 vcc, s48, v164
	v_ashrrev_i32_e32 v163, 31, v162
	s_and_saveexec_b64 s[2:3], vcc
	s_xor_b64 s[2:3], exec, s[2:3]
	v_add_u32_e32 v238, 0xffffe000, v164
	v_lshlrev_b64 v[166:167], 12, v[238:239]
	v_mov_b32_e32 v165, v239
	v_lshl_add_u64 v[168:169], s[14:15], 0, v[166:167]
	v_lshlrev_b64 v[170:171], 12, v[164:165]
	v_mov_b64_e32 v[166:167], v[162:163]
	s_andn2_saveexec_b64 s[2:3], s[2:3]
	v_ashrrev_i32_e32 v165, 31, v164
	v_lshlrev_b64 v[170:171], 12, v[164:165]
	v_lshl_add_u64 v[168:169], s[12:13], 0, v[170:171]
	v_mov_b64_e32 v[166:167], 0
	s_or_b64 exec, exec, s[2:3]
	v_and_b32_e32 v165, 0xc0, v172
	v_lshrrev_b32_e32 v172, 2, v172
	s_lshl_b32 s2, s36, 8
	v_and_b32_e32 v172, 12, v172
	v_or3_b32 v172, v165, s2, v172
	v_ashrrev_i32_e32 v173, 31, v172
	v_lshl_add_u64 v[176:177], v[166:167], 2, s[20:21]
	v_lshlrev_b64 v[166:167], 2, v[172:173]
	v_lshl_add_u64 v[180:181], v[168:169], 0, v[166:167]
	v_lshl_add_u64 v[182:183], v[176:177], 0, v[166:167]
	v_lshl_add_u64 v[168:169], s[4:5], 0, v[170:171]
	v_lshl_add_u64 v[184:185], v[168:169], 0, v[166:167]
	s_mov_b64 s[2:3], 0x10000
	global_load_dwordx4 v[162:165], v[182:183], off
	global_load_dwordx4 v[166:169], v[182:183], off offset:64
	global_load_dwordx4 v[170:173], v[182:183], off offset:128
	global_load_dwordx4 v[174:177], v[182:183], off offset:192
	global_load_dwordx4 v[186:189], v[180:181], off
	global_load_dwordx4 v[190:193], v[180:181], off offset:64
	global_load_dwordx4 v[194:197], v[180:181], off offset:128
	global_load_dwordx4 v[198:201], v[180:181], off offset:192
	v_lshl_add_u64 v[180:181], v[180:181], 0, s[2:3]
	global_load_dwordx4 v[202:205], v[180:181], off
	global_load_dwordx4 v[206:209], v[180:181], off offset:64
	global_load_dwordx4 v[210:213], v[180:181], off offset:128
	global_load_dwordx4 v[214:217], v[180:181], off offset:192
	v_lshl_add_u64 v[180:181], v[180:181], 0, s[2:3]
	global_load_dwordx4 v[218:221], v[180:181], off
	global_load_dwordx4 v[222:225], v[180:181], off offset:64
	global_load_dwordx4 v[226:229], v[180:181], off offset:128
	global_load_dwordx4 v[2:5], v[180:181], off offset:192
	v_lshl_add_u64 v[180:181], v[180:181], 0, s[2:3]
	global_load_dwordx4 v[6:9], v[180:181], off
	global_load_dwordx4 v[10:13], v[180:181], off offset:64
	global_load_dwordx4 v[14:17], v[180:181], off offset:128
	global_load_dwordx4 v[18:21], v[180:181], off offset:192
	v_lshl_add_u64 v[180:181], v[180:181], 0, s[2:3]
	s_waitcnt vmcnt(12)
	v_pk_fma_f32 v[160:161], v[160:161], v[164:165], v[188:189]
	v_pk_fma_f32 v[158:159], v[158:159], v[162:163], v[186:187]
	global_store_dwordx4 v[184:185], v[158:161], off
	v_pk_fma_f32 v[156:157], v[156:157], v[168:169], v[192:193]
	v_pk_fma_f32 v[154:155], v[154:155], v[166:167], v[190:191]
	global_store_dwordx4 v[184:185], v[154:157], off offset:64
	v_pk_fma_f32 v[152:153], v[152:153], v[172:173], v[196:197]
	v_pk_fma_f32 v[150:151], v[150:151], v[170:171], v[194:195]
	global_store_dwordx4 v[184:185], v[150:153], off offset:128
	v_pk_fma_f32 v[148:149], v[148:149], v[176:177], v[200:201]
	v_pk_fma_f32 v[146:147], v[146:147], v[174:175], v[198:199]
	global_store_dwordx4 v[184:185], v[146:149], off offset:192
	v_lshl_add_u64 v[184:185], v[184:185], 0, s[2:3]
	s_waitcnt vmcnt(12)
	v_pk_fma_f32 v[144:145], v[144:145], v[164:165], v[204:205]
	v_pk_fma_f32 v[142:143], v[142:143], v[162:163], v[202:203]
	global_store_dwordx4 v[184:185], v[142:145], off
	v_pk_fma_f32 v[140:141], v[140:141], v[168:169], v[208:209]
	v_pk_fma_f32 v[138:139], v[138:139], v[166:167], v[206:207]
	global_store_dwordx4 v[184:185], v[138:141], off offset:64
	v_pk_fma_f32 v[136:137], v[136:137], v[172:173], v[212:213]
	v_pk_fma_f32 v[134:135], v[134:135], v[170:171], v[210:211]
	global_store_dwordx4 v[184:185], v[134:137], off offset:128
	v_pk_fma_f32 v[132:133], v[132:133], v[176:177], v[216:217]
	v_pk_fma_f32 v[130:131], v[130:131], v[174:175], v[214:215]
	global_store_dwordx4 v[184:185], v[130:133], off offset:192
	v_lshl_add_u64 v[184:185], v[184:185], 0, s[2:3]
	global_load_dwordx4 v[186:189], v[180:181], off
	global_load_dwordx4 v[190:193], v[180:181], off offset:64
	global_load_dwordx4 v[194:197], v[180:181], off offset:128
	global_load_dwordx4 v[198:201], v[180:181], off offset:192
	v_lshl_add_u64 v[180:181], v[180:181], 0, s[2:3]
	global_load_dwordx4 v[202:205], v[180:181], off
	global_load_dwordx4 v[206:209], v[180:181], off offset:64
	global_load_dwordx4 v[210:213], v[180:181], off offset:128
	global_load_dwordx4 v[214:217], v[180:181], off offset:192
	v_lshl_add_u64 v[180:181], v[180:181], 0, s[2:3]
	s_waitcnt vmcnt(20)
	v_pk_fma_f32 v[128:129], v[128:129], v[164:165], v[220:221]
	v_pk_fma_f32 v[126:127], v[126:127], v[162:163], v[218:219]
	global_store_dwordx4 v[184:185], v[126:129], off
	v_pk_fma_f32 v[124:125], v[124:125], v[168:169], v[224:225]
	v_pk_fma_f32 v[122:123], v[122:123], v[166:167], v[222:223]
	global_store_dwordx4 v[184:185], v[122:125], off offset:64
	v_pk_fma_f32 v[120:121], v[120:121], v[172:173], v[228:229]
	v_pk_fma_f32 v[118:119], v[118:119], v[170:171], v[226:227]
	global_store_dwordx4 v[184:185], v[118:121], off offset:128
	v_pk_fma_f32 v[116:117], v[116:117], v[176:177], v[4:5]
	v_pk_fma_f32 v[114:115], v[114:115], v[174:175], v[2:3]
	global_store_dwordx4 v[184:185], v[114:117], off offset:192
	v_lshl_add_u64 v[184:185], v[184:185], 0, s[2:3]
	s_waitcnt vmcnt(20)
	v_pk_fma_f32 v[112:113], v[112:113], v[164:165], v[8:9]
	v_pk_fma_f32 v[110:111], v[110:111], v[162:163], v[6:7]
	global_store_dwordx4 v[184:185], v[110:113], off
	v_pk_fma_f32 v[108:109], v[108:109], v[168:169], v[12:13]
	v_pk_fma_f32 v[106:107], v[106:107], v[166:167], v[10:11]
	global_store_dwordx4 v[184:185], v[106:109], off offset:64
	v_pk_fma_f32 v[104:105], v[104:105], v[172:173], v[16:17]
	v_pk_fma_f32 v[102:103], v[102:103], v[170:171], v[14:15]
	global_store_dwordx4 v[184:185], v[102:105], off offset:128
	v_pk_fma_f32 v[84:85], v[84:85], v[176:177], v[20:21]
	v_pk_fma_f32 v[82:83], v[82:83], v[174:175], v[18:19]
	global_store_dwordx4 v[184:185], v[82:85], off offset:192
	v_lshl_add_u64 v[184:185], v[184:185], 0, s[2:3]
	global_load_dwordx4 v[218:221], v[180:181], off
	global_load_dwordx4 v[222:225], v[180:181], off offset:64
	global_load_dwordx4 v[226:229], v[180:181], off offset:128
	global_load_dwordx4 v[2:5], v[180:181], off offset:192
	v_lshl_add_u64 v[180:181], v[180:181], 0, s[2:3]
	global_load_dwordx4 v[6:9], v[180:181], off
	global_load_dwordx4 v[10:13], v[180:181], off offset:64
	global_load_dwordx4 v[14:17], v[180:181], off offset:128
	global_load_dwordx4 v[18:21], v[180:181], off offset:192
	v_lshl_add_u64 v[180:181], v[180:181], 0, s[2:3]
	s_waitcnt vmcnt(20)
	v_pk_fma_f32 v[100:101], v[100:101], v[164:165], v[188:189]
	v_pk_fma_f32 v[98:99], v[98:99], v[162:163], v[186:187]
	global_store_dwordx4 v[184:185], v[98:101], off
	v_pk_fma_f32 v[96:97], v[96:97], v[168:169], v[192:193]
	v_pk_fma_f32 v[94:95], v[94:95], v[166:167], v[190:191]
	global_store_dwordx4 v[184:185], v[94:97], off offset:64
	v_pk_fma_f32 v[92:93], v[92:93], v[172:173], v[196:197]
	v_pk_fma_f32 v[90:91], v[90:91], v[170:171], v[194:195]
	global_store_dwordx4 v[184:185], v[90:93], off offset:128
	v_pk_fma_f32 v[88:89], v[88:89], v[176:177], v[200:201]
	v_pk_fma_f32 v[86:87], v[86:87], v[174:175], v[198:199]
	global_store_dwordx4 v[184:185], v[86:89], off offset:192
	v_lshl_add_u64 v[184:185], v[184:185], 0, s[2:3]
	s_waitcnt vmcnt(20)
	v_pk_fma_f32 v[80:81], v[80:81], v[164:165], v[204:205]
	v_pk_fma_f32 v[78:79], v[78:79], v[162:163], v[202:203]
	global_store_dwordx4 v[184:185], v[78:81], off
	v_pk_fma_f32 v[76:77], v[76:77], v[168:169], v[208:209]
	v_pk_fma_f32 v[74:75], v[74:75], v[166:167], v[206:207]
	global_store_dwordx4 v[184:185], v[74:77], off offset:64
	v_pk_fma_f32 v[72:73], v[72:73], v[172:173], v[212:213]
	v_pk_fma_f32 v[70:71], v[70:71], v[170:171], v[210:211]
	global_store_dwordx4 v[184:185], v[70:73], off offset:128
	v_pk_fma_f32 v[68:69], v[68:69], v[176:177], v[216:217]
	v_pk_fma_f32 v[66:67], v[66:67], v[174:175], v[214:215]
	global_store_dwordx4 v[184:185], v[66:69], off offset:192
	v_lshl_add_u64 v[184:185], v[184:185], 0, s[2:3]
	s_waitcnt vmcnt(12)
	v_pk_fma_f32 v[64:65], v[64:65], v[164:165], v[220:221]
	v_pk_fma_f32 v[62:63], v[62:63], v[162:163], v[218:219]
	global_store_dwordx4 v[184:185], v[62:65], off
	v_pk_fma_f32 v[60:61], v[60:61], v[168:169], v[224:225]
	v_pk_fma_f32 v[58:59], v[58:59], v[166:167], v[222:223]
	global_store_dwordx4 v[184:185], v[58:61], off offset:64
	v_pk_fma_f32 v[56:57], v[56:57], v[172:173], v[228:229]
	v_pk_fma_f32 v[54:55], v[54:55], v[170:171], v[226:227]
	global_store_dwordx4 v[184:185], v[54:57], off offset:128
	v_pk_fma_f32 v[52:53], v[52:53], v[176:177], v[4:5]
	v_pk_fma_f32 v[50:51], v[50:51], v[174:175], v[2:3]
	global_store_dwordx4 v[184:185], v[50:53], off offset:192
	v_lshl_add_u64 v[184:185], v[184:185], 0, s[2:3]
	s_waitcnt vmcnt(12)
	v_pk_fma_f32 v[48:49], v[48:49], v[164:165], v[8:9]
	v_pk_fma_f32 v[46:47], v[46:47], v[162:163], v[6:7]
	global_store_dwordx4 v[184:185], v[46:49], off
	v_pk_fma_f32 v[44:45], v[44:45], v[168:169], v[12:13]
	v_pk_fma_f32 v[42:43], v[42:43], v[166:167], v[10:11]
	global_store_dwordx4 v[184:185], v[42:45], off offset:64
	v_pk_fma_f32 v[40:41], v[40:41], v[172:173], v[16:17]
	v_pk_fma_f32 v[38:39], v[38:39], v[170:171], v[14:15]
	global_store_dwordx4 v[184:185], v[38:41], off offset:128
	v_pk_fma_f32 v[36:37], v[36:37], v[176:177], v[20:21]
	v_pk_fma_f32 v[34:35], v[34:35], v[174:175], v[18:19]
	global_store_dwordx4 v[184:185], v[34:37], off offset:192
	v_lshl_add_u64 v[184:185], v[184:185], 0, s[2:3]
	s_nop 1
	s_add_i32 s49, s49, s11
	s_cmp_gt_i32 s49, 31
	v_mov_b32_e32 v37, 0
	s_cbranch_scc1 .LBB0_958
	s_ashr_i32 s3, s49, 31
	s_lshr_b32 s3, s3, 27
	s_add_i32 s3, s49, s3
	s_ashr_i32 s3, s3, 5
	s_mov_b32 s2, s10
	s_lshl_b32 s22, s3, 6
	s_lshl_b32 s23, s49, 1
	s_sub_i32 s22, s23, s22
	s_and_b32 s2, s2, 7
	s_and_b32 s22, s22, -8
	s_lshl_b32 s3, s3, 2
	s_and_b32 s23, s49, 3
	s_or_b32 s36, s3, s23
	s_or_b32 s38, s2, s22
	s_branch .LBB0_958

.LBB0_1326:
	s_add_i32 s50, s50, 2
	s_cmp_lg_u32 s50, 44
	s_waitcnt lgkmcnt(0)
	s_mov_b32 s98, 1
	s_cbranch_scc1 .LBB0_1301
	s_mov_b32 s98, 0
	v_mfma_f32_16x16x32_bf16 v[98:101], v[210:213], v[178:181], v[98:101]
	v_mfma_f32_16x16x32_bf16 v[94:97], v[214:217], v[178:181], v[94:97]
	v_mfma_f32_16x16x32_bf16 v[90:93], v[218:221], v[178:181], v[90:93]
	v_mfma_f32_16x16x32_bf16 v[86:89], v[222:225], v[178:181], v[86:89]
	v_mfma_f32_16x16x32_bf16 v[78:81], v[210:213], v[182:185], v[78:81]
	v_mfma_f32_16x16x32_bf16 v[74:77], v[214:217], v[182:185], v[74:77]
	v_mfma_f32_16x16x32_bf16 v[70:73], v[218:221], v[182:185], v[70:73]
	v_mfma_f32_16x16x32_bf16 v[66:69], v[222:225], v[182:185], v[66:69]
	v_mfma_f32_16x16x32_bf16 v[62:65], v[210:213], v[186:189], v[62:65]
	v_mfma_f32_16x16x32_bf16 v[58:61], v[214:217], v[186:189], v[58:61]
	v_mfma_f32_16x16x32_bf16 v[54:57], v[218:221], v[186:189], v[54:57]
	v_mfma_f32_16x16x32_bf16 v[50:53], v[222:225], v[186:189], v[50:53]
	v_mfma_f32_16x16x32_bf16 v[46:49], v[210:213], v[190:193], v[46:49]
	v_mfma_f32_16x16x32_bf16 v[42:45], v[214:217], v[190:193], v[42:45]
	v_mfma_f32_16x16x32_bf16 v[38:41], v[218:221], v[190:193], v[38:41]
	v_mfma_f32_16x16x32_bf16 v[34:37], v[222:225], v[190:193], v[34:37]
	s_nop 7
	s_nop 7
	v_mov_b32_e32 v172, v0
	s_nop 0
	v_ashrrev_i32_e32 v162, 1, v172
	v_and_b32_e32 v162, 0xffffff80, v162
	v_lshl_add_u32 v162, s36, 8, v162
	v_and_or_b32 v164, v172, 15, v162
	v_add_u32_e32 v162, 0xffffe000, v162
	v_ashrrev_i32_e32 v162, 11, v162
	v_mad_i32_i24 v162, v162, s45, s45
	v_cmp_lt_i32_e32 vcc, s46, v164
	v_ashrrev_i32_e32 v163, 31, v162
	s_and_saveexec_b64 s[2:3], vcc
	s_xor_b64 s[2:3], exec, s[2:3]
	v_add_u32_e32 v238, 0xffffe000, v164
	v_lshlrev_b64 v[166:167], 12, v[238:239]
	v_mov_b32_e32 v165, v239
	v_lshl_add_u64 v[168:169], s[12:13], 0, v[166:167]
	v_lshlrev_b64 v[170:171], 12, v[164:165]
	v_mov_b64_e32 v[166:167], v[162:163]
	s_andn2_saveexec_b64 s[2:3], s[2:3]
	v_ashrrev_i32_e32 v165, 31, v164
	v_lshlrev_b64 v[170:171], 12, v[164:165]
	v_lshl_add_u64 v[168:169], s[4:5], 0, v[170:171]
	v_mov_b64_e32 v[166:167], 0
	s_or_b64 exec, exec, s[2:3]
	v_and_b32_e32 v165, 0xc0, v172
	v_lshrrev_b32_e32 v172, 2, v172
	s_lshl_b32 s2, s34, 8
	v_and_b32_e32 v172, 12, v172
	v_or3_b32 v172, v165, s2, v172
	v_ashrrev_i32_e32 v173, 31, v172
	v_lshl_add_u64 v[176:177], v[166:167], 2, s[14:15]
	v_lshlrev_b64 v[166:167], 2, v[172:173]
	v_lshl_add_u64 v[180:181], v[168:169], 0, v[166:167]
	v_lshl_add_u64 v[182:183], v[176:177], 0, v[166:167]
	v_lshl_add_u64 v[168:169], s[4:5], 0, v[170:171]
	v_lshl_add_u64 v[184:185], v[168:169], 0, v[166:167]
	s_mov_b64 s[2:3], 0x10000
	global_load_dwordx4 v[162:165], v[182:183], off
	global_load_dwordx4 v[166:169], v[182:183], off offset:64
	global_load_dwordx4 v[170:173], v[182:183], off offset:128
	global_load_dwordx4 v[174:177], v[182:183], off offset:192
	global_load_dwordx4 v[186:189], v[180:181], off
	global_load_dwordx4 v[190:193], v[180:181], off offset:64
	global_load_dwordx4 v[194:197], v[180:181], off offset:128
	global_load_dwordx4 v[198:201], v[180:181], off offset:192
	v_lshl_add_u64 v[180:181], v[180:181], 0, s[2:3]
	global_load_dwordx4 v[202:205], v[180:181], off
	global_load_dwordx4 v[206:209], v[180:181], off offset:64
	global_load_dwordx4 v[210:213], v[180:181], off offset:128
	global_load_dwordx4 v[214:217], v[180:181], off offset:192
	v_lshl_add_u64 v[180:181], v[180:181], 0, s[2:3]
	global_load_dwordx4 v[218:221], v[180:181], off
	global_load_dwordx4 v[222:225], v[180:181], off offset:64
	global_load_dwordx4 v[226:229], v[180:181], off offset:128
	global_load_dwordx4 v[2:5], v[180:181], off offset:192
	v_lshl_add_u64 v[180:181], v[180:181], 0, s[2:3]
	global_load_dwordx4 v[6:9], v[180:181], off
	global_load_dwordx4 v[10:13], v[180:181], off offset:64
	global_load_dwordx4 v[14:17], v[180:181], off offset:128
	global_load_dwordx4 v[18:21], v[180:181], off offset:192
	v_lshl_add_u64 v[180:181], v[180:181], 0, s[2:3]
	s_waitcnt vmcnt(12)
	v_pk_fma_f32 v[160:161], v[160:161], v[164:165], v[188:189]
	v_pk_fma_f32 v[158:159], v[158:159], v[162:163], v[186:187]
	global_store_dwordx4 v[184:185], v[158:161], off
	v_pk_fma_f32 v[156:157], v[156:157], v[168:169], v[192:193]
	v_pk_fma_f32 v[154:155], v[154:155], v[166:167], v[190:191]
	global_store_dwordx4 v[184:185], v[154:157], off offset:64
	v_pk_fma_f32 v[152:153], v[152:153], v[172:173], v[196:197]
	v_pk_fma_f32 v[150:151], v[150:151], v[170:171], v[194:195]
	global_store_dwordx4 v[184:185], v[150:153], off offset:128
	v_pk_fma_f32 v[148:149], v[148:149], v[176:177], v[200:201]
	v_pk_fma_f32 v[146:147], v[146:147], v[174:175], v[198:199]
	global_store_dwordx4 v[184:185], v[146:149], off offset:192
	v_lshl_add_u64 v[184:185], v[184:185], 0, s[2:3]
	s_waitcnt vmcnt(12)
	v_pk_fma_f32 v[144:145], v[144:145], v[164:165], v[204:205]
	v_pk_fma_f32 v[142:143], v[142:143], v[162:163], v[202:203]
	global_store_dwordx4 v[184:185], v[142:145], off
	v_pk_fma_f32 v[140:141], v[140:141], v[168:169], v[208:209]
	v_pk_fma_f32 v[138:139], v[138:139], v[166:167], v[206:207]
	global_store_dwordx4 v[184:185], v[138:141], off offset:64
	v_pk_fma_f32 v[136:137], v[136:137], v[172:173], v[212:213]
	v_pk_fma_f32 v[134:135], v[134:135], v[170:171], v[210:211]
	global_store_dwordx4 v[184:185], v[134:137], off offset:128
	v_pk_fma_f32 v[132:133], v[132:133], v[176:177], v[216:217]
	v_pk_fma_f32 v[130:131], v[130:131], v[174:175], v[214:215]
	global_store_dwordx4 v[184:185], v[130:133], off offset:192
	v_lshl_add_u64 v[184:185], v[184:185], 0, s[2:3]
	global_load_dwordx4 v[186:189], v[180:181], off
	global_load_dwordx4 v[190:193], v[180:181], off offset:64
	global_load_dwordx4 v[194:197], v[180:181], off offset:128
	global_load_dwordx4 v[198:201], v[180:181], off offset:192
	v_lshl_add_u64 v[180:181], v[180:181], 0, s[2:3]
	global_load_dwordx4 v[202:205], v[180:181], off
	global_load_dwordx4 v[206:209], v[180:181], off offset:64
	global_load_dwordx4 v[210:213], v[180:181], off offset:128
	global_load_dwordx4 v[214:217], v[180:181], off offset:192
	v_lshl_add_u64 v[180:181], v[180:181], 0, s[2:3]
	s_waitcnt vmcnt(20)
	v_pk_fma_f32 v[128:129], v[128:129], v[164:165], v[220:221]
	v_pk_fma_f32 v[126:127], v[126:127], v[162:163], v[218:219]
	global_store_dwordx4 v[184:185], v[126:129], off
	v_pk_fma_f32 v[124:125], v[124:125], v[168:169], v[224:225]
	v_pk_fma_f32 v[122:123], v[122:123], v[166:167], v[222:223]
	global_store_dwordx4 v[184:185], v[122:125], off offset:64
	v_pk_fma_f32 v[120:121], v[120:121], v[172:173], v[228:229]
	v_pk_fma_f32 v[118:119], v[118:119], v[170:171], v[226:227]
	global_store_dwordx4 v[184:185], v[118:121], off offset:128
	v_pk_fma_f32 v[116:117], v[116:117], v[176:177], v[4:5]
	v_pk_fma_f32 v[114:115], v[114:115], v[174:175], v[2:3]
	global_store_dwordx4 v[184:185], v[114:117], off offset:192
	v_lshl_add_u64 v[184:185], v[184:185], 0, s[2:3]
	s_waitcnt vmcnt(20)
	v_pk_fma_f32 v[112:113], v[112:113], v[164:165], v[8:9]
	v_pk_fma_f32 v[110:111], v[110:111], v[162:163], v[6:7]
	global_store_dwordx4 v[184:185], v[110:113], off
	v_pk_fma_f32 v[108:109], v[108:109], v[168:169], v[12:13]
	v_pk_fma_f32 v[106:107], v[106:107], v[166:167], v[10:11]
	global_store_dwordx4 v[184:185], v[106:109], off offset:64
	v_pk_fma_f32 v[104:105], v[104:105], v[172:173], v[16:17]
	v_pk_fma_f32 v[102:103], v[102:103], v[170:171], v[14:15]
	global_store_dwordx4 v[184:185], v[102:105], off offset:128
	v_pk_fma_f32 v[84:85], v[84:85], v[176:177], v[20:21]
	v_pk_fma_f32 v[82:83], v[82:83], v[174:175], v[18:19]
	global_store_dwordx4 v[184:185], v[82:85], off offset:192
	v_lshl_add_u64 v[184:185], v[184:185], 0, s[2:3]
	global_load_dwordx4 v[218:221], v[180:181], off
	global_load_dwordx4 v[222:225], v[180:181], off offset:64
	global_load_dwordx4 v[226:229], v[180:181], off offset:128
	global_load_dwordx4 v[2:5], v[180:181], off offset:192
	v_lshl_add_u64 v[180:181], v[180:181], 0, s[2:3]
	global_load_dwordx4 v[6:9], v[180:181], off
	global_load_dwordx4 v[10:13], v[180:181], off offset:64
	global_load_dwordx4 v[14:17], v[180:181], off offset:128
	global_load_dwordx4 v[18:21], v[180:181], off offset:192
	v_lshl_add_u64 v[180:181], v[180:181], 0, s[2:3]
	s_waitcnt vmcnt(20)
	v_pk_fma_f32 v[100:101], v[100:101], v[164:165], v[188:189]
	v_pk_fma_f32 v[98:99], v[98:99], v[162:163], v[186:187]
	global_store_dwordx4 v[184:185], v[98:101], off
	v_pk_fma_f32 v[96:97], v[96:97], v[168:169], v[192:193]
	v_pk_fma_f32 v[94:95], v[94:95], v[166:167], v[190:191]
	global_store_dwordx4 v[184:185], v[94:97], off offset:64
	v_pk_fma_f32 v[92:93], v[92:93], v[172:173], v[196:197]
	v_pk_fma_f32 v[90:91], v[90:91], v[170:171], v[194:195]
	global_store_dwordx4 v[184:185], v[90:93], off offset:128
	v_pk_fma_f32 v[88:89], v[88:89], v[176:177], v[200:201]
	v_pk_fma_f32 v[86:87], v[86:87], v[174:175], v[198:199]
	global_store_dwordx4 v[184:185], v[86:89], off offset:192
	v_lshl_add_u64 v[184:185], v[184:185], 0, s[2:3]
	s_waitcnt vmcnt(20)
	v_pk_fma_f32 v[80:81], v[80:81], v[164:165], v[204:205]
	v_pk_fma_f32 v[78:79], v[78:79], v[162:163], v[202:203]
	global_store_dwordx4 v[184:185], v[78:81], off
	v_pk_fma_f32 v[76:77], v[76:77], v[168:169], v[208:209]
	v_pk_fma_f32 v[74:75], v[74:75], v[166:167], v[206:207]
	global_store_dwordx4 v[184:185], v[74:77], off offset:64
	v_pk_fma_f32 v[72:73], v[72:73], v[172:173], v[212:213]
	v_pk_fma_f32 v[70:71], v[70:71], v[170:171], v[210:211]
	global_store_dwordx4 v[184:185], v[70:73], off offset:128
	v_pk_fma_f32 v[68:69], v[68:69], v[176:177], v[216:217]
	v_pk_fma_f32 v[66:67], v[66:67], v[174:175], v[214:215]
	global_store_dwordx4 v[184:185], v[66:69], off offset:192
	v_lshl_add_u64 v[184:185], v[184:185], 0, s[2:3]
	s_waitcnt vmcnt(12)
	v_pk_fma_f32 v[64:65], v[64:65], v[164:165], v[220:221]
	v_pk_fma_f32 v[62:63], v[62:63], v[162:163], v[218:219]
	global_store_dwordx4 v[184:185], v[62:65], off
	v_pk_fma_f32 v[60:61], v[60:61], v[168:169], v[224:225]
	v_pk_fma_f32 v[58:59], v[58:59], v[166:167], v[222:223]
	global_store_dwordx4 v[184:185], v[58:61], off offset:64
	v_pk_fma_f32 v[56:57], v[56:57], v[172:173], v[228:229]
	v_pk_fma_f32 v[54:55], v[54:55], v[170:171], v[226:227]
	global_store_dwordx4 v[184:185], v[54:57], off offset:128
	v_pk_fma_f32 v[52:53], v[52:53], v[176:177], v[4:5]
	v_pk_fma_f32 v[50:51], v[50:51], v[174:175], v[2:3]
	global_store_dwordx4 v[184:185], v[50:53], off offset:192
	v_lshl_add_u64 v[184:185], v[184:185], 0, s[2:3]
	s_waitcnt vmcnt(12)
	v_pk_fma_f32 v[48:49], v[48:49], v[164:165], v[8:9]
	v_pk_fma_f32 v[46:47], v[46:47], v[162:163], v[6:7]
	global_store_dwordx4 v[184:185], v[46:49], off
	v_pk_fma_f32 v[44:45], v[44:45], v[168:169], v[12:13]
	v_pk_fma_f32 v[42:43], v[42:43], v[166:167], v[10:11]
	global_store_dwordx4 v[184:185], v[42:45], off offset:64
	v_pk_fma_f32 v[40:41], v[40:41], v[172:173], v[16:17]
	v_pk_fma_f32 v[38:39], v[38:39], v[170:171], v[14:15]
	global_store_dwordx4 v[184:185], v[38:41], off offset:128
	v_pk_fma_f32 v[36:37], v[36:37], v[176:177], v[20:21]
	v_pk_fma_f32 v[34:35], v[34:35], v[174:175], v[18:19]
	global_store_dwordx4 v[184:185], v[34:37], off offset:192
	v_lshl_add_u64 v[184:185], v[184:185], 0, s[2:3]
	s_nop 1
	s_add_i32 s47, s47, s11
	s_cmp_gt_i32 s47, 31
	v_mov_b32_e32 v37, 0
	s_cbranch_scc1 .LBB0_1300
	s_ashr_i32 s3, s47, 31
	s_lshr_b32 s3, s3, 27
	s_add_i32 s3, s47, s3
	s_ashr_i32 s3, s3, 5
	s_mov_b32 s2, s10
	s_lshl_b32 s20, s3, 6
	s_lshl_b32 s21, s47, 1
	s_sub_i32 s20, s21, s20
	s_and_b32 s2, s2, 7
	s_and_b32 s20, s20, -8
	s_lshl_b32 s3, s3, 2
	s_and_b32 s21, s47, 3
	s_or_b32 s34, s3, s21
	s_or_b32 s36, s2, s20
	s_branch .LBB0_1300

.LBB0_2227:
	s_add_i32 s50, s50, 2
	s_cmp_lg_u32 s50, 16
	s_waitcnt lgkmcnt(0)
	s_mov_b32 s98, 1
	s_cbranch_scc1 .LBB0_2202
	s_mov_b32 s98, 0
	v_mfma_f32_16x16x32_bf16 v[98:101], v[210:213], v[178:181], v[98:101]
	v_mfma_f32_16x16x32_bf16 v[94:97], v[214:217], v[178:181], v[94:97]
	v_mfma_f32_16x16x32_bf16 v[90:93], v[218:221], v[178:181], v[90:93]
	v_mfma_f32_16x16x32_bf16 v[86:89], v[222:225], v[178:181], v[86:89]
	v_mfma_f32_16x16x32_bf16 v[78:81], v[210:213], v[182:185], v[78:81]
	v_mfma_f32_16x16x32_bf16 v[74:77], v[214:217], v[182:185], v[74:77]
	v_mfma_f32_16x16x32_bf16 v[70:73], v[218:221], v[182:185], v[70:73]
	v_mfma_f32_16x16x32_bf16 v[66:69], v[222:225], v[182:185], v[66:69]
	v_mfma_f32_16x16x32_bf16 v[62:65], v[210:213], v[186:189], v[62:65]
	v_mfma_f32_16x16x32_bf16 v[58:61], v[214:217], v[186:189], v[58:61]
	v_mfma_f32_16x16x32_bf16 v[54:57], v[218:221], v[186:189], v[54:57]
	v_mfma_f32_16x16x32_bf16 v[50:53], v[222:225], v[186:189], v[50:53]
	v_mfma_f32_16x16x32_bf16 v[46:49], v[210:213], v[190:193], v[46:49]
	v_mfma_f32_16x16x32_bf16 v[42:45], v[214:217], v[190:193], v[42:45]
	v_mfma_f32_16x16x32_bf16 v[38:41], v[218:221], v[190:193], v[38:41]
	v_mfma_f32_16x16x32_bf16 v[34:37], v[222:225], v[190:193], v[34:37]
	s_nop 7
	s_nop 7
	v_mov_b32_e32 v172, v0
	s_nop 0
	v_ashrrev_i32_e32 v162, 1, v172
	v_and_b32_e32 v162, 0xffffff80, v162
	v_lshl_add_u32 v162, s36, 8, v162
	v_and_or_b32 v164, v172, 15, v162
	v_add_u32_e32 v162, 0xffffe000, v162
	v_ashrrev_i32_e32 v162, 11, v162
	v_mad_i32_i24 v162, v162, s45, s45
	v_cmp_lt_i32_e32 vcc, s46, v164
	v_ashrrev_i32_e32 v163, 31, v162
	s_and_saveexec_b64 s[2:3], vcc
	s_xor_b64 s[2:3], exec, s[2:3]
	v_add_u32_e32 v238, 0xffffe000, v164
	v_lshlrev_b64 v[166:167], 12, v[238:239]
	v_mov_b32_e32 v165, v239
	v_lshl_add_u64 v[168:169], s[12:13], 0, v[166:167]
	v_lshlrev_b64 v[170:171], 12, v[164:165]
	v_mov_b64_e32 v[166:167], v[162:163]
	s_andn2_saveexec_b64 s[2:3], s[2:3]
	v_ashrrev_i32_e32 v165, 31, v164
	v_lshlrev_b64 v[170:171], 12, v[164:165]
	v_lshl_add_u64 v[168:169], s[4:5], 0, v[170:171]
	v_mov_b64_e32 v[166:167], 0
	s_or_b64 exec, exec, s[2:3]
	v_and_b32_e32 v165, 0xc0, v172
	v_lshrrev_b32_e32 v172, 2, v172
	s_lshl_b32 s2, s34, 8
	v_and_b32_e32 v172, 12, v172
	v_or3_b32 v172, v165, s2, v172
	v_ashrrev_i32_e32 v173, 31, v172
	v_lshl_add_u64 v[176:177], v[166:167], 2, s[14:15]
	v_lshlrev_b64 v[166:167], 2, v[172:173]
	v_lshl_add_u64 v[180:181], v[168:169], 0, v[166:167]
	v_lshl_add_u64 v[182:183], v[176:177], 0, v[166:167]
	v_lshl_add_u64 v[168:169], s[4:5], 0, v[170:171]
	v_lshl_add_u64 v[184:185], v[168:169], 0, v[166:167]
	s_mov_b64 s[2:3], 0x10000
	global_load_dwordx4 v[162:165], v[182:183], off
	global_load_dwordx4 v[166:169], v[182:183], off offset:64
	global_load_dwordx4 v[170:173], v[182:183], off offset:128
	global_load_dwordx4 v[174:177], v[182:183], off offset:192
	global_load_dwordx4 v[186:189], v[180:181], off
	global_load_dwordx4 v[190:193], v[180:181], off offset:64
	global_load_dwordx4 v[194:197], v[180:181], off offset:128
	global_load_dwordx4 v[198:201], v[180:181], off offset:192
	v_lshl_add_u64 v[180:181], v[180:181], 0, s[2:3]
	global_load_dwordx4 v[202:205], v[180:181], off
	global_load_dwordx4 v[206:209], v[180:181], off offset:64
	global_load_dwordx4 v[210:213], v[180:181], off offset:128
	global_load_dwordx4 v[214:217], v[180:181], off offset:192
	v_lshl_add_u64 v[180:181], v[180:181], 0, s[2:3]
	global_load_dwordx4 v[218:221], v[180:181], off
	global_load_dwordx4 v[222:225], v[180:181], off offset:64
	global_load_dwordx4 v[226:229], v[180:181], off offset:128
	global_load_dwordx4 v[2:5], v[180:181], off offset:192
	v_lshl_add_u64 v[180:181], v[180:181], 0, s[2:3]
	global_load_dwordx4 v[6:9], v[180:181], off
	global_load_dwordx4 v[10:13], v[180:181], off offset:64
	global_load_dwordx4 v[14:17], v[180:181], off offset:128
	global_load_dwordx4 v[18:21], v[180:181], off offset:192
	v_lshl_add_u64 v[180:181], v[180:181], 0, s[2:3]
	s_waitcnt vmcnt(12)
	v_pk_fma_f32 v[160:161], v[160:161], v[164:165], v[188:189]
	v_pk_fma_f32 v[158:159], v[158:159], v[162:163], v[186:187]
	global_store_dwordx4 v[184:185], v[158:161], off
	v_pk_fma_f32 v[156:157], v[156:157], v[168:169], v[192:193]
	v_pk_fma_f32 v[154:155], v[154:155], v[166:167], v[190:191]
	global_store_dwordx4 v[184:185], v[154:157], off offset:64
	v_pk_fma_f32 v[152:153], v[152:153], v[172:173], v[196:197]
	v_pk_fma_f32 v[150:151], v[150:151], v[170:171], v[194:195]
	global_store_dwordx4 v[184:185], v[150:153], off offset:128
	v_pk_fma_f32 v[148:149], v[148:149], v[176:177], v[200:201]
	v_pk_fma_f32 v[146:147], v[146:147], v[174:175], v[198:199]
	global_store_dwordx4 v[184:185], v[146:149], off offset:192
	v_lshl_add_u64 v[184:185], v[184:185], 0, s[2:3]
	s_waitcnt vmcnt(12)
	v_pk_fma_f32 v[144:145], v[144:145], v[164:165], v[204:205]
	v_pk_fma_f32 v[142:143], v[142:143], v[162:163], v[202:203]
	global_store_dwordx4 v[184:185], v[142:145], off
	v_pk_fma_f32 v[140:141], v[140:141], v[168:169], v[208:209]
	v_pk_fma_f32 v[138:139], v[138:139], v[166:167], v[206:207]
	global_store_dwordx4 v[184:185], v[138:141], off offset:64
	v_pk_fma_f32 v[136:137], v[136:137], v[172:173], v[212:213]
	v_pk_fma_f32 v[134:135], v[134:135], v[170:171], v[210:211]
	global_store_dwordx4 v[184:185], v[134:137], off offset:128
	v_pk_fma_f32 v[132:133], v[132:133], v[176:177], v[216:217]
	v_pk_fma_f32 v[130:131], v[130:131], v[174:175], v[214:215]
	global_store_dwordx4 v[184:185], v[130:133], off offset:192
	v_lshl_add_u64 v[184:185], v[184:185], 0, s[2:3]
	global_load_dwordx4 v[186:189], v[180:181], off
	global_load_dwordx4 v[190:193], v[180:181], off offset:64
	global_load_dwordx4 v[194:197], v[180:181], off offset:128
	global_load_dwordx4 v[198:201], v[180:181], off offset:192
	v_lshl_add_u64 v[180:181], v[180:181], 0, s[2:3]
	global_load_dwordx4 v[202:205], v[180:181], off
	global_load_dwordx4 v[206:209], v[180:181], off offset:64
	global_load_dwordx4 v[210:213], v[180:181], off offset:128
	global_load_dwordx4 v[214:217], v[180:181], off offset:192
	v_lshl_add_u64 v[180:181], v[180:181], 0, s[2:3]
	s_waitcnt vmcnt(20)
	v_pk_fma_f32 v[128:129], v[128:129], v[164:165], v[220:221]
	v_pk_fma_f32 v[126:127], v[126:127], v[162:163], v[218:219]
	global_store_dwordx4 v[184:185], v[126:129], off
	v_pk_fma_f32 v[124:125], v[124:125], v[168:169], v[224:225]
	v_pk_fma_f32 v[122:123], v[122:123], v[166:167], v[222:223]
	global_store_dwordx4 v[184:185], v[122:125], off offset:64
	v_pk_fma_f32 v[120:121], v[120:121], v[172:173], v[228:229]
	v_pk_fma_f32 v[118:119], v[118:119], v[170:171], v[226:227]
	global_store_dwordx4 v[184:185], v[118:121], off offset:128
	v_pk_fma_f32 v[116:117], v[116:117], v[176:177], v[4:5]
	v_pk_fma_f32 v[114:115], v[114:115], v[174:175], v[2:3]
	global_store_dwordx4 v[184:185], v[114:117], off offset:192
	v_lshl_add_u64 v[184:185], v[184:185], 0, s[2:3]
	s_waitcnt vmcnt(20)
	v_pk_fma_f32 v[112:113], v[112:113], v[164:165], v[8:9]
	v_pk_fma_f32 v[110:111], v[110:111], v[162:163], v[6:7]
	global_store_dwordx4 v[184:185], v[110:113], off
	v_pk_fma_f32 v[108:109], v[108:109], v[168:169], v[12:13]
	v_pk_fma_f32 v[106:107], v[106:107], v[166:167], v[10:11]
	global_store_dwordx4 v[184:185], v[106:109], off offset:64
	v_pk_fma_f32 v[104:105], v[104:105], v[172:173], v[16:17]
	v_pk_fma_f32 v[102:103], v[102:103], v[170:171], v[14:15]
	global_store_dwordx4 v[184:185], v[102:105], off offset:128
	v_pk_fma_f32 v[84:85], v[84:85], v[176:177], v[20:21]
	v_pk_fma_f32 v[82:83], v[82:83], v[174:175], v[18:19]
	global_store_dwordx4 v[184:185], v[82:85], off offset:192
	v_lshl_add_u64 v[184:185], v[184:185], 0, s[2:3]
	global_load_dwordx4 v[218:221], v[180:181], off
	global_load_dwordx4 v[222:225], v[180:181], off offset:64
	global_load_dwordx4 v[226:229], v[180:181], off offset:128
	global_load_dwordx4 v[2:5], v[180:181], off offset:192
	v_lshl_add_u64 v[180:181], v[180:181], 0, s[2:3]
	global_load_dwordx4 v[6:9], v[180:181], off
	global_load_dwordx4 v[10:13], v[180:181], off offset:64
	global_load_dwordx4 v[14:17], v[180:181], off offset:128
	global_load_dwordx4 v[18:21], v[180:181], off offset:192
	v_lshl_add_u64 v[180:181], v[180:181], 0, s[2:3]
	s_waitcnt vmcnt(20)
	v_pk_fma_f32 v[100:101], v[100:101], v[164:165], v[188:189]
	v_pk_fma_f32 v[98:99], v[98:99], v[162:163], v[186:187]
	global_store_dwordx4 v[184:185], v[98:101], off
	v_pk_fma_f32 v[96:97], v[96:97], v[168:169], v[192:193]
	v_pk_fma_f32 v[94:95], v[94:95], v[166:167], v[190:191]
	global_store_dwordx4 v[184:185], v[94:97], off offset:64
	v_pk_fma_f32 v[92:93], v[92:93], v[172:173], v[196:197]
	v_pk_fma_f32 v[90:91], v[90:91], v[170:171], v[194:195]
	global_store_dwordx4 v[184:185], v[90:93], off offset:128
	v_pk_fma_f32 v[88:89], v[88:89], v[176:177], v[200:201]
	v_pk_fma_f32 v[86:87], v[86:87], v[174:175], v[198:199]
	global_store_dwordx4 v[184:185], v[86:89], off offset:192
	v_lshl_add_u64 v[184:185], v[184:185], 0, s[2:3]
	s_waitcnt vmcnt(20)
	v_pk_fma_f32 v[80:81], v[80:81], v[164:165], v[204:205]
	v_pk_fma_f32 v[78:79], v[78:79], v[162:163], v[202:203]
	global_store_dwordx4 v[184:185], v[78:81], off
	v_pk_fma_f32 v[76:77], v[76:77], v[168:169], v[208:209]
	v_pk_fma_f32 v[74:75], v[74:75], v[166:167], v[206:207]
	global_store_dwordx4 v[184:185], v[74:77], off offset:64
	v_pk_fma_f32 v[72:73], v[72:73], v[172:173], v[212:213]
	v_pk_fma_f32 v[70:71], v[70:71], v[170:171], v[210:211]
	global_store_dwordx4 v[184:185], v[70:73], off offset:128
	v_pk_fma_f32 v[68:69], v[68:69], v[176:177], v[216:217]
	v_pk_fma_f32 v[66:67], v[66:67], v[174:175], v[214:215]
	global_store_dwordx4 v[184:185], v[66:69], off offset:192
	v_lshl_add_u64 v[184:185], v[184:185], 0, s[2:3]
	s_waitcnt vmcnt(12)
	v_pk_fma_f32 v[64:65], v[64:65], v[164:165], v[220:221]
	v_pk_fma_f32 v[62:63], v[62:63], v[162:163], v[218:219]
	global_store_dwordx4 v[184:185], v[62:65], off
	v_pk_fma_f32 v[60:61], v[60:61], v[168:169], v[224:225]
	v_pk_fma_f32 v[58:59], v[58:59], v[166:167], v[222:223]
	global_store_dwordx4 v[184:185], v[58:61], off offset:64
	v_pk_fma_f32 v[56:57], v[56:57], v[172:173], v[228:229]
	v_pk_fma_f32 v[54:55], v[54:55], v[170:171], v[226:227]
	global_store_dwordx4 v[184:185], v[54:57], off offset:128
	v_pk_fma_f32 v[52:53], v[52:53], v[176:177], v[4:5]
	v_pk_fma_f32 v[50:51], v[50:51], v[174:175], v[2:3]
	global_store_dwordx4 v[184:185], v[50:53], off offset:192
	v_lshl_add_u64 v[184:185], v[184:185], 0, s[2:3]
	s_waitcnt vmcnt(12)
	v_pk_fma_f32 v[48:49], v[48:49], v[164:165], v[8:9]
	v_pk_fma_f32 v[46:47], v[46:47], v[162:163], v[6:7]
	global_store_dwordx4 v[184:185], v[46:49], off
	v_pk_fma_f32 v[44:45], v[44:45], v[168:169], v[12:13]
	v_pk_fma_f32 v[42:43], v[42:43], v[166:167], v[10:11]
	global_store_dwordx4 v[184:185], v[42:45], off offset:64
	v_pk_fma_f32 v[40:41], v[40:41], v[172:173], v[16:17]
	v_pk_fma_f32 v[38:39], v[38:39], v[170:171], v[14:15]
	global_store_dwordx4 v[184:185], v[38:41], off offset:128
	v_pk_fma_f32 v[36:37], v[36:37], v[176:177], v[20:21]
	v_pk_fma_f32 v[34:35], v[34:35], v[174:175], v[18:19]
	global_store_dwordx4 v[184:185], v[34:37], off offset:192
	v_lshl_add_u64 v[184:185], v[184:185], 0, s[2:3]
	s_nop 1
	s_add_i32 s47, s47, s11
	s_cmp_gt_i32 s47, 31
	v_mov_b32_e32 v37, 0
	s_cbranch_scc1 .LBB0_2201
	s_ashr_i32 s3, s47, 31
	s_lshr_b32 s3, s3, 27
	s_add_i32 s3, s47, s3
	s_ashr_i32 s3, s3, 5
	s_mov_b32 s2, s10
	s_lshl_b32 s20, s3, 6
	s_lshl_b32 s21, s47, 1
	s_sub_i32 s20, s21, s20
	s_and_b32 s2, s2, 7
	s_and_b32 s20, s20, -8
	s_lshl_b32 s3, s3, 2
	s_and_b32 s21, s47, 3
	s_or_b32 s34, s3, s21
	s_or_b32 s36, s2, s20
	s_branch .LBB0_2201

.LBB0_2569:
	s_add_i32 s42, s42, 2
	s_cmp_lg_u32 s42, 44
	s_waitcnt lgkmcnt(0)
	s_mov_b32 s98, 1
	s_cbranch_scc1 .LBB0_2544
	s_mov_b32 s98, 0
	v_mfma_f32_16x16x32_bf16 v[98:101], v[210:213], v[178:181], v[98:101]
	v_mfma_f32_16x16x32_bf16 v[94:97], v[214:217], v[178:181], v[94:97]
	v_mfma_f32_16x16x32_bf16 v[90:93], v[218:221], v[178:181], v[90:93]
	v_mfma_f32_16x16x32_bf16 v[86:89], v[222:225], v[178:181], v[86:89]
	v_mfma_f32_16x16x32_bf16 v[78:81], v[210:213], v[182:185], v[78:81]
	v_mfma_f32_16x16x32_bf16 v[74:77], v[214:217], v[182:185], v[74:77]
	v_mfma_f32_16x16x32_bf16 v[70:73], v[218:221], v[182:185], v[70:73]
	v_mfma_f32_16x16x32_bf16 v[66:69], v[222:225], v[182:185], v[66:69]
	v_mfma_f32_16x16x32_bf16 v[62:65], v[210:213], v[186:189], v[62:65]
	v_mfma_f32_16x16x32_bf16 v[58:61], v[214:217], v[186:189], v[58:61]
	v_mfma_f32_16x16x32_bf16 v[54:57], v[218:221], v[186:189], v[54:57]
	v_mfma_f32_16x16x32_bf16 v[50:53], v[222:225], v[186:189], v[50:53]
	v_mfma_f32_16x16x32_bf16 v[46:49], v[210:213], v[190:193], v[46:49]
	v_mfma_f32_16x16x32_bf16 v[42:45], v[214:217], v[190:193], v[42:45]
	v_mfma_f32_16x16x32_bf16 v[38:41], v[218:221], v[190:193], v[38:41]
	v_mfma_f32_16x16x32_bf16 v[34:37], v[222:225], v[190:193], v[34:37]
	s_nop 7
	s_nop 7
	v_mov_b32_e32 v172, v0
	s_nop 0
	v_ashrrev_i32_e32 v162, 1, v172
	v_and_b32_e32 v162, 0xffffff80, v162
	v_lshl_add_u32 v162, s27, 8, v162
	v_and_or_b32 v164, v172, 15, v162
	v_add_u32_e32 v162, 0xffffe000, v162
	v_ashrrev_i32_e32 v162, 11, v162
	v_mad_i32_i24 v162, v162, s37, s37
	v_cmp_lt_i32_e32 vcc, s38, v164
	v_ashrrev_i32_e32 v163, 31, v162
	s_and_saveexec_b64 s[0:1], vcc
	s_xor_b64 s[0:1], exec, s[0:1]
	v_add_u32_e32 v238, 0xffffe000, v164
	v_lshlrev_b64 v[166:167], 12, v[238:239]
	v_mov_b32_e32 v165, v239
	v_lshl_add_u64 v[168:169], s[2:3], 0, v[166:167]
	v_lshlrev_b64 v[170:171], 12, v[164:165]
	v_mov_b64_e32 v[166:167], v[162:163]
	s_andn2_saveexec_b64 s[0:1], s[0:1]
	v_ashrrev_i32_e32 v165, 31, v164
	v_lshlrev_b64 v[170:171], 12, v[164:165]
	v_lshl_add_u64 v[168:169], s[4:5], 0, v[170:171]
	v_mov_b64_e32 v[166:167], 0
	s_or_b64 exec, exec, s[0:1]
	v_and_b32_e32 v165, 0xc0, v172
	v_lshrrev_b32_e32 v172, 2, v172
	s_lshl_b32 s0, s25, 8
	v_and_b32_e32 v172, 12, v172
	v_or3_b32 v172, v165, s0, v172
	v_ashrrev_i32_e32 v173, 31, v172
	v_lshl_add_u64 v[176:177], v[166:167], 2, s[8:9]
	v_lshlrev_b64 v[166:167], 2, v[172:173]
	v_lshl_add_u64 v[180:181], v[168:169], 0, v[166:167]
	v_lshl_add_u64 v[182:183], v[176:177], 0, v[166:167]
	v_lshl_add_u64 v[168:169], s[4:5], 0, v[170:171]
	v_lshl_add_u64 v[184:185], v[168:169], 0, v[166:167]
	s_mov_b64 s[2:3], 0x10000
	global_load_dwordx4 v[162:165], v[182:183], off
	global_load_dwordx4 v[166:169], v[182:183], off offset:64
	global_load_dwordx4 v[170:173], v[182:183], off offset:128
	global_load_dwordx4 v[174:177], v[182:183], off offset:192
	global_load_dwordx4 v[186:189], v[180:181], off
	global_load_dwordx4 v[190:193], v[180:181], off offset:64
	global_load_dwordx4 v[194:197], v[180:181], off offset:128
	global_load_dwordx4 v[198:201], v[180:181], off offset:192
	v_lshl_add_u64 v[180:181], v[180:181], 0, s[2:3]
	global_load_dwordx4 v[202:205], v[180:181], off
	global_load_dwordx4 v[206:209], v[180:181], off offset:64
	global_load_dwordx4 v[210:213], v[180:181], off offset:128
	global_load_dwordx4 v[214:217], v[180:181], off offset:192
	v_lshl_add_u64 v[180:181], v[180:181], 0, s[2:3]
	global_load_dwordx4 v[218:221], v[180:181], off
	global_load_dwordx4 v[222:225], v[180:181], off offset:64
	global_load_dwordx4 v[226:229], v[180:181], off offset:128
	global_load_dwordx4 v[2:5], v[180:181], off offset:192
	v_lshl_add_u64 v[180:181], v[180:181], 0, s[2:3]
	global_load_dwordx4 v[6:9], v[180:181], off
	global_load_dwordx4 v[10:13], v[180:181], off offset:64
	global_load_dwordx4 v[14:17], v[180:181], off offset:128
	global_load_dwordx4 v[18:21], v[180:181], off offset:192
	v_lshl_add_u64 v[180:181], v[180:181], 0, s[2:3]
	s_waitcnt vmcnt(12)
	v_pk_fma_f32 v[160:161], v[160:161], v[164:165], v[188:189]
	v_pk_fma_f32 v[158:159], v[158:159], v[162:163], v[186:187]
	global_store_dwordx4 v[184:185], v[158:161], off
	v_pk_fma_f32 v[156:157], v[156:157], v[168:169], v[192:193]
	v_pk_fma_f32 v[154:155], v[154:155], v[166:167], v[190:191]
	global_store_dwordx4 v[184:185], v[154:157], off offset:64
	v_pk_fma_f32 v[152:153], v[152:153], v[172:173], v[196:197]
	v_pk_fma_f32 v[150:151], v[150:151], v[170:171], v[194:195]
	global_store_dwordx4 v[184:185], v[150:153], off offset:128
	v_pk_fma_f32 v[148:149], v[148:149], v[176:177], v[200:201]
	v_pk_fma_f32 v[146:147], v[146:147], v[174:175], v[198:199]
	global_store_dwordx4 v[184:185], v[146:149], off offset:192
	v_lshl_add_u64 v[184:185], v[184:185], 0, s[2:3]
	s_waitcnt vmcnt(12)
	v_pk_fma_f32 v[144:145], v[144:145], v[164:165], v[204:205]
	v_pk_fma_f32 v[142:143], v[142:143], v[162:163], v[202:203]
	global_store_dwordx4 v[184:185], v[142:145], off
	v_pk_fma_f32 v[140:141], v[140:141], v[168:169], v[208:209]
	v_pk_fma_f32 v[138:139], v[138:139], v[166:167], v[206:207]
	global_store_dwordx4 v[184:185], v[138:141], off offset:64
	v_pk_fma_f32 v[136:137], v[136:137], v[172:173], v[212:213]
	v_pk_fma_f32 v[134:135], v[134:135], v[170:171], v[210:211]
	global_store_dwordx4 v[184:185], v[134:137], off offset:128
	v_pk_fma_f32 v[132:133], v[132:133], v[176:177], v[216:217]
	v_pk_fma_f32 v[130:131], v[130:131], v[174:175], v[214:215]
	global_store_dwordx4 v[184:185], v[130:133], off offset:192
	v_lshl_add_u64 v[184:185], v[184:185], 0, s[2:3]
	global_load_dwordx4 v[186:189], v[180:181], off
	global_load_dwordx4 v[190:193], v[180:181], off offset:64
	global_load_dwordx4 v[194:197], v[180:181], off offset:128
	global_load_dwordx4 v[198:201], v[180:181], off offset:192
	v_lshl_add_u64 v[180:181], v[180:181], 0, s[2:3]
	global_load_dwordx4 v[202:205], v[180:181], off
	global_load_dwordx4 v[206:209], v[180:181], off offset:64
	global_load_dwordx4 v[210:213], v[180:181], off offset:128
	global_load_dwordx4 v[214:217], v[180:181], off offset:192
	v_lshl_add_u64 v[180:181], v[180:181], 0, s[2:3]
	s_waitcnt vmcnt(20)
	v_pk_fma_f32 v[128:129], v[128:129], v[164:165], v[220:221]
	v_pk_fma_f32 v[126:127], v[126:127], v[162:163], v[218:219]
	global_store_dwordx4 v[184:185], v[126:129], off
	v_pk_fma_f32 v[124:125], v[124:125], v[168:169], v[224:225]
	v_pk_fma_f32 v[122:123], v[122:123], v[166:167], v[222:223]
	global_store_dwordx4 v[184:185], v[122:125], off offset:64
	v_pk_fma_f32 v[120:121], v[120:121], v[172:173], v[228:229]
	v_pk_fma_f32 v[118:119], v[118:119], v[170:171], v[226:227]
	global_store_dwordx4 v[184:185], v[118:121], off offset:128
	v_pk_fma_f32 v[116:117], v[116:117], v[176:177], v[4:5]
	v_pk_fma_f32 v[114:115], v[114:115], v[174:175], v[2:3]
	global_store_dwordx4 v[184:185], v[114:117], off offset:192
	v_lshl_add_u64 v[184:185], v[184:185], 0, s[2:3]
	s_waitcnt vmcnt(20)
	v_pk_fma_f32 v[112:113], v[112:113], v[164:165], v[8:9]
	v_pk_fma_f32 v[110:111], v[110:111], v[162:163], v[6:7]
	global_store_dwordx4 v[184:185], v[110:113], off
	v_pk_fma_f32 v[108:109], v[108:109], v[168:169], v[12:13]
	v_pk_fma_f32 v[106:107], v[106:107], v[166:167], v[10:11]
	global_store_dwordx4 v[184:185], v[106:109], off offset:64
	v_pk_fma_f32 v[104:105], v[104:105], v[172:173], v[16:17]
	v_pk_fma_f32 v[102:103], v[102:103], v[170:171], v[14:15]
	global_store_dwordx4 v[184:185], v[102:105], off offset:128
	v_pk_fma_f32 v[84:85], v[84:85], v[176:177], v[20:21]
	v_pk_fma_f32 v[82:83], v[82:83], v[174:175], v[18:19]
	global_store_dwordx4 v[184:185], v[82:85], off offset:192
	v_lshl_add_u64 v[184:185], v[184:185], 0, s[2:3]
	global_load_dwordx4 v[218:221], v[180:181], off
	global_load_dwordx4 v[222:225], v[180:181], off offset:64
	global_load_dwordx4 v[226:229], v[180:181], off offset:128
	global_load_dwordx4 v[2:5], v[180:181], off offset:192
	v_lshl_add_u64 v[180:181], v[180:181], 0, s[2:3]
	global_load_dwordx4 v[6:9], v[180:181], off
	global_load_dwordx4 v[10:13], v[180:181], off offset:64
	global_load_dwordx4 v[14:17], v[180:181], off offset:128
	global_load_dwordx4 v[18:21], v[180:181], off offset:192
	v_lshl_add_u64 v[180:181], v[180:181], 0, s[2:3]
	s_waitcnt vmcnt(20)
	v_pk_fma_f32 v[100:101], v[100:101], v[164:165], v[188:189]
	v_pk_fma_f32 v[98:99], v[98:99], v[162:163], v[186:187]
	global_store_dwordx4 v[184:185], v[98:101], off
	v_pk_fma_f32 v[96:97], v[96:97], v[168:169], v[192:193]
	v_pk_fma_f32 v[94:95], v[94:95], v[166:167], v[190:191]
	global_store_dwordx4 v[184:185], v[94:97], off offset:64
	v_pk_fma_f32 v[92:93], v[92:93], v[172:173], v[196:197]
	v_pk_fma_f32 v[90:91], v[90:91], v[170:171], v[194:195]
	global_store_dwordx4 v[184:185], v[90:93], off offset:128
	v_pk_fma_f32 v[88:89], v[88:89], v[176:177], v[200:201]
	v_pk_fma_f32 v[86:87], v[86:87], v[174:175], v[198:199]
	global_store_dwordx4 v[184:185], v[86:89], off offset:192
	v_lshl_add_u64 v[184:185], v[184:185], 0, s[2:3]
	s_waitcnt vmcnt(20)
	v_pk_fma_f32 v[80:81], v[80:81], v[164:165], v[204:205]
	v_pk_fma_f32 v[78:79], v[78:79], v[162:163], v[202:203]
	global_store_dwordx4 v[184:185], v[78:81], off
	v_pk_fma_f32 v[76:77], v[76:77], v[168:169], v[208:209]
	v_pk_fma_f32 v[74:75], v[74:75], v[166:167], v[206:207]
	global_store_dwordx4 v[184:185], v[74:77], off offset:64
	v_pk_fma_f32 v[72:73], v[72:73], v[172:173], v[212:213]
	v_pk_fma_f32 v[70:71], v[70:71], v[170:171], v[210:211]
	global_store_dwordx4 v[184:185], v[70:73], off offset:128
	v_pk_fma_f32 v[68:69], v[68:69], v[176:177], v[216:217]
	v_pk_fma_f32 v[66:67], v[66:67], v[174:175], v[214:215]
	global_store_dwordx4 v[184:185], v[66:69], off offset:192
	v_lshl_add_u64 v[184:185], v[184:185], 0, s[2:3]
	s_waitcnt vmcnt(12)
	v_pk_fma_f32 v[64:65], v[64:65], v[164:165], v[220:221]
	v_pk_fma_f32 v[62:63], v[62:63], v[162:163], v[218:219]
	global_store_dwordx4 v[184:185], v[62:65], off
	v_pk_fma_f32 v[60:61], v[60:61], v[168:169], v[224:225]
	v_pk_fma_f32 v[58:59], v[58:59], v[166:167], v[222:223]
	global_store_dwordx4 v[184:185], v[58:61], off offset:64
	v_pk_fma_f32 v[56:57], v[56:57], v[172:173], v[228:229]
	v_pk_fma_f32 v[54:55], v[54:55], v[170:171], v[226:227]
	global_store_dwordx4 v[184:185], v[54:57], off offset:128
	v_pk_fma_f32 v[52:53], v[52:53], v[176:177], v[4:5]
	v_pk_fma_f32 v[50:51], v[50:51], v[174:175], v[2:3]
	global_store_dwordx4 v[184:185], v[50:53], off offset:192
	v_lshl_add_u64 v[184:185], v[184:185], 0, s[2:3]
	s_waitcnt vmcnt(12)
	v_pk_fma_f32 v[48:49], v[48:49], v[164:165], v[8:9]
	v_pk_fma_f32 v[46:47], v[46:47], v[162:163], v[6:7]
	global_store_dwordx4 v[184:185], v[46:49], off
	v_pk_fma_f32 v[44:45], v[44:45], v[168:169], v[12:13]
	v_pk_fma_f32 v[42:43], v[42:43], v[166:167], v[10:11]
	global_store_dwordx4 v[184:185], v[42:45], off offset:64
	v_pk_fma_f32 v[40:41], v[40:41], v[172:173], v[16:17]
	v_pk_fma_f32 v[38:39], v[38:39], v[170:171], v[14:15]
	global_store_dwordx4 v[184:185], v[38:41], off offset:128
	v_pk_fma_f32 v[36:37], v[36:37], v[176:177], v[20:21]
	v_pk_fma_f32 v[34:35], v[34:35], v[174:175], v[18:19]
	global_store_dwordx4 v[184:185], v[34:37], off offset:192
	v_lshl_add_u64 v[184:185], v[184:185], 0, s[2:3]
	s_nop 1
	s_add_i32 s39, s39, s11
	s_cmp_gt_i32 s39, 31
	v_mov_b32_e32 v37, 0
	s_cbranch_scc1 .LBB0_2543
	s_ashr_i32 s1, s39, 31
	s_lshr_b32 s1, s1, 27
	s_add_i32 s1, s39, s1
	s_ashr_i32 s1, s1, 5
	s_mov_b32 s0, s10
	s_lshl_b32 s12, s1, 6
	s_lshl_b32 s13, s39, 1
	s_sub_i32 s12, s13, s12
	s_and_b32 s0, s0, 7
	s_and_b32 s12, s12, -8
	s_lshl_b32 s1, s1, 2
	s_and_b32 s13, s39, 3
	s_or_b32 s25, s1, s13
	s_or_b32 s27, s0, s12
	s_branch .LBB0_2543
